# E8b + attention item prologue no longer drains the Q-fragment loads before issuing the first K/V tile loads
# speedup vs baseline: 1.0103x; 1.0103x over previous
; DI void attn_phase(const Params& p, const u16* proj, const char* prep, u16* obuf, char* smem) {
;     ...
;     bf16x8 Qf[8];
;     {
;       const size_t qrow = qrow0 + ((qt * 32 < nq) ? qt * 32 : 0) + l31;
;       const u16* qp = proj + qrow * 8192 + (2 * h + jh) * 128 + hh * 8;
; #pragma unroll
;       for (int s = 0; s < 8; ++s) Qf[s] = ld16(qp + s * 16);
; #pragma unroll
;       for (int s = 0; s < 8; ++s) asm volatile("" : "+v"(Qf[s]));
;     }
;     u32x4 kr[4], vr[4];
;     auto gload = [&](int kt) {
; #pragma unroll
;       for (int ii = 0; ii < 4; ++ii) {
;         const int id = tid + 512 * ii;
;         const int jl = id >> 10, key = (id >> 4) & 63, ch = id & 15;
;         kr[ii] = *reinterpret_cast<const u32x4*>(kbase + jl * khs + (size_t)(kt * 64 + key) * kstride + ch * 8);
;         const int vd = id >> 3, cv = id & 7;
;         vr[ii] = *reinterpret_cast<const u32x4*>(vtbase + (size_t)vd * vtstride + kt * 64 + cv * 8);
;       }
;     };
;     auto sstore = [&](int buf) {
;       u16* Ks = lds + buf * BUFE; u16* Vt = Ks + 2 * 64 * 136;
; #pragma unroll
;       for (int ii = 0; ii < 4; ++ii) {
;         const int id = tid + 512 * ii;
;         const int jl = id >> 10, key = (id >> 4) & 63, ch = id & 15;
;         *reinterpret_cast<u32x4*>(Ks + (jl * 64 + key) * 136 + ch * 8) = kr[ii];
;         const int vd = id >> 3, cv = id & 7;
;         *reinterpret_cast<u32x4*>(Vt + vd * 72 + cv * 8) = vr[ii];
;       }
;     };
;     float m = -1e30f, l = 0.f;
;     f32x16 O[4];
; #pragma unroll
;     for (int vt = 0; vt < 4; ++vt) O[vt] = zero16();
;     ...
;     const bool grpB = vh != 0;
;     gload(0);
;     __syncthreads();
;     sstore(0);
;     __syncthreads();
;     if (nt > 1) gload(1);
.LBB0_1028:
	s_cmp_lt_u32 s96, s64
	s_cselect_b32 s15, s96, 0
	s_add_u32 s18, s15, s48
	s_addc_u32 s19, 0, s49
	v_lshl_add_u64 v[0:1], s[18:19], 0, v[160:161]
	v_lshlrev_b64 v[0:1], 14, v[0:1]
	v_lshl_add_u64 v[0:1], s[56:57], 0, v[0:1]
	s_or_b32 s78, s84, s97
	v_lshl_add_u64 v[0:1], s[78:79], 1, v[0:1]
	v_lshlrev_b32_e32 v180, 1, v164
	v_mov_b32_e32 v181, v163
	v_lshl_add_u64 v[0:1], v[0:1], 0, v[180:181]
	global_load_dwordx4 v[96:99], v[0:1], off
	global_load_dwordx4 v[100:103], v[0:1], off offset:32
	global_load_dwordx4 v[104:107], v[0:1], off offset:64
	global_load_dwordx4 v[108:111], v[0:1], off offset:96
	global_load_dwordx4 v[112:115], v[0:1], off offset:128
	global_load_dwordx4 v[116:119], v[0:1], off offset:160
	global_load_dwordx4 v[120:123], v[0:1], off offset:192
	global_load_dwordx4 v[124:127], v[0:1], off offset:224
	v_mul_hi_i32_i24_e32 v1, s16, v167
	v_mul_i32_i24_e32 v0, s16, v167
	v_mul_u32_u24_e32 v8, s86, v169
	v_mov_b32_e32 v9, v163
	v_mad_i64_i32 v[2:3], s[18:19], s14, v168, 0
	v_mul_hi_i32_i24_e32 v5, s16, v171
	v_mul_i32_i24_e32 v4, s16, v171
	v_mul_u32_u24_e32 v10, s86, v173
	v_mad_i64_i32 v[6:7], s[18:19], s14, v172, 0
	v_mul_hi_i32_i24_e32 v13, s16, v175
	v_mul_i32_i24_e32 v12, s16, v175
	v_mad_i64_i32 v[14:15], s[18:19], s14, v174, 0
	v_mul_hi_i32_i24_e32 v17, s16, v177
	v_mul_i32_i24_e32 v16, s16, v177
	v_mul_u32_u24_e32 v18, s86, v200
	v_mad_i64_i32 v[20:21], s[14:15], s14, v176, 0
	v_lshl_add_u64 v[0:1], v[0:1], 1, s[10:11]
	v_lshlrev_b32_e32 v8, 1, v8
	v_lshlrev_b32_e32 v162, 1, v166
	v_lshlrev_b32_e32 v182, 1, v170
	v_mov_b32_e32 v183, v163
	v_mov_b32_e32 v11, v163
	v_mov_b32_e32 v19, v163
	v_lshl_add_u64 v[22:23], v[2:3], 1, s[12:13]
	v_lshl_add_u64 v[2:3], v[4:5], 1, s[10:11]
	v_lshlrev_b32_e32 v10, 1, v10
	v_lshl_add_u64 v[24:25], v[6:7], 1, s[12:13]
	v_lshl_add_u64 v[4:5], v[12:13], 1, s[10:11]
	v_lshl_add_u64 v[12:13], v[14:15], 1, s[12:13]
	v_lshl_add_u64 v[6:7], v[16:17], 1, s[10:11]
	v_lshlrev_b32_e32 v18, 1, v18
	v_lshl_add_u64 v[14:15], v[20:21], 1, s[12:13]
	v_lshl_add_u64 v[16:17], v[0:1], 0, v[8:9]
	v_lshl_add_u64 v[10:11], v[2:3], 0, v[10:11]
	v_lshl_add_u64 v[8:9], v[4:5], 0, v[8:9]
	v_lshl_add_u64 v[188:189], v[12:13], 0, v[182:183]
	v_lshl_add_u64 v[12:13], v[6:7], 0, v[18:19]
	v_lshl_add_u64 v[190:191], v[14:15], 0, v[182:183]
	v_lshl_add_u64 v[14:15], v[16:17], 0, v[162:163]
	v_lshl_add_u64 v[184:185], v[22:23], 0, v[182:183]
	v_lshl_add_u64 v[186:187], v[24:25], 0, v[182:183]
	v_lshl_add_u64 v[10:11], v[10:11], 0, v[162:163]
	v_lshl_add_u64 v[8:9], v[8:9], 0, v[162:163]
	v_lshl_add_u64 v[12:13], v[12:13], 0, v[162:163]
	s_cmp_lt_u32 s65, 2
	global_load_dwordx4 v[128:131], v[14:15], off
	global_load_dwordx4 v[132:135], v[184:185], off
	global_load_dwordx4 v[136:139], v[10:11], off
	global_load_dwordx4 v[140:143], v[186:187], off
	global_load_dwordx4 v[144:147], v[8:9], off
	global_load_dwordx4 v[148:151], v[188:189], off
	global_load_dwordx4 v[152:155], v[12:13], off
	global_load_dwordx4 v[156:159], v[190:191], off
	s_barrier
	s_waitcnt vmcnt(7)
	ds_write_b128 v202, v[128:131]
	s_waitcnt vmcnt(6)
	ds_write_b128 v204, v[132:135] offset:34816
	s_waitcnt vmcnt(5)
	ds_write_b128 v206, v[136:139]
	s_waitcnt vmcnt(4)
	ds_write_b128 v210, v[140:143] offset:34816
	s_waitcnt vmcnt(3)
	ds_write_b128 v212, v[144:147]
	s_waitcnt vmcnt(2)
	ds_write_b128 v214, v[148:151] offset:34816
	s_waitcnt vmcnt(1)
	ds_write_b128 v216, v[152:155]
	s_waitcnt vmcnt(0)
	ds_write_b128 v218, v[156:159] offset:34816
	s_waitcnt lgkmcnt(0)
	s_barrier
	s_cbranch_scc1 .LBB0_1030
	v_mul_u32_u24_e32 v8, s86, v219
	v_lshlrev_b32_e32 v8, 1, v8
	v_mov_b32_e32 v9, v163
	v_mul_u32_u24_e32 v12, s86, v220
	v_lshl_add_u64 v[10:11], v[0:1], 0, v[8:9]
	v_lshlrev_b32_e32 v12, 1, v12
	v_mov_b32_e32 v13, v163
	v_lshl_add_u64 v[10:11], v[10:11], 0, v[162:163]
	v_lshl_add_u64 v[12:13], v[2:3], 0, v[12:13]
	v_lshl_add_u64 v[12:13], v[12:13], 0, v[162:163]
	global_load_dwordx4 v[128:131], v[10:11], off
	global_load_dwordx4 v[136:139], v[12:13], off
	global_load_dwordx4 v[132:135], v[184:185], off offset:128
	global_load_dwordx4 v[140:143], v[186:187], off offset:128
	v_mul_u32_u24_e32 v10, s86, v221
	v_lshl_add_u64 v[8:9], v[4:5], 0, v[8:9]
	v_lshlrev_b32_e32 v10, 1, v10
	v_mov_b32_e32 v11, v163
	v_lshl_add_u64 v[8:9], v[8:9], 0, v[162:163]
	v_lshl_add_u64 v[10:11], v[6:7], 0, v[10:11]
	v_lshl_add_u64 v[10:11], v[10:11], 0, v[162:163]
	global_load_dwordx4 v[144:147], v[8:9], off
	global_load_dwordx4 v[152:155], v[10:11], off
	global_load_dwordx4 v[148:151], v[188:189], off offset:128
	global_load_dwordx4 v[156:159], v[190:191], off offset:128
